# comb13 + packed-to-scalar split (guide 7.5): the 6 v_pk_add_f32 between MFMAs in each attention main loop become pairs of v_add_f32
# speedup vs baseline: 1.0045x; 1.0045x over previous
; #define LAS __attribute__((address_space(3)))
; __device__ __forceinline__ unsigned cvt_pk(float lo, float hi) { unsigned r; asm volatile("v_cvt_pk_bf16_f32 %0, %1, %2" : "=v"(r) : "v"(lo), "v"(hi)); return r; }
; __device__ __forceinline__ void attn_unit(LAS unsigned char* lds, int b, int h, int q0, int kbeg, int ntiles, const bf16_t* Q, const bf16_t* K, const bf16_t* Vt, bf16_t* cat) {
;     ...
;         const LAS unsigned char* kb = lds + (buf ^ 1) * AK_BYTES + r32 * (KP * 2) + hi * 16;
;         f32x16 pn0, pn1;
; #pragma unroll
;         for (int r = 0; r < 16; ++r) { pn0[r] = 0.f; pn1[r] = 0.f; }
;         float ps = 0.f; u32x4 pw[4];
;         bf16x8 ka = *(const LAS bf16x8*)(kb), kbb = *(const LAS bf16x8*)(kb + 32 * (KP * 2));
; #pragma unroll
;         for (int ds = 0; ds < 12; ++ds) {
;             bf16x8 na = ka, nb = kbb;
;             if (ds < 11) { na = *(const LAS bf16x8*)(kb + (ds + 1) * 32); nb = *(const LAS bf16x8*)(kb + 32 * (KP * 2) + (ds + 1) * 32); }
;             pn0 = __builtin_amdgcn_mfma_f32_32x32x16_bf16(ka, qf[ds], pn0, 0, 0, 0);
;             pn1 = __builtin_amdgcn_mfma_f32_32x32x16_bf16(kbb, qf[ds], pn1, 0, 0, 0);
;             if (ds < 8) {
;                 float e[4];
; #pragma unroll
;                 for (int j = 0; j < 4; ++j) { const float v = ds < 4 ? pc0[4 * ds + j] : pc1[4 * (ds - 4) + j]; e[j] = __builtin_amdgcn_exp2f(v - mrun); }
;                 ps += (e[0] + e[1]) + (e[2] + e[3]);
;                 const unsigned w0 = cvt_pk(e[0], e[1]), w1 = cvt_pk(e[2], e[3]);
;                 if ((ds & 1) == 0) { pw[ds >> 1].x = w0; pw[ds >> 1].y = w1; } else { pw[ds >> 1].z = w0; pw[ds >> 1].w = w1; }
;             }
;             ka = na; kbb = nb;
;             __builtin_amdgcn_sched_barrier(0);
;         }
.LBB0_814:
	s_xor_b32 s6, s5, 1
	s_mul_i32 s7, s6, 0x6400
	v_add_u32_e32 v236, s7, v228
	ds_read_b128 v[98:101], v236
	v_sub_f32_e32 v82, v82, v230
	v_exp_f32_e32 v197, v82
	v_sub_f32_e32 v82, v84, v230
	v_exp_f32_e32 v201, v82
	v_sub_f32_e32 v82, v85, v230
	v_exp_f32_e32 v233, v82
	v_sub_f32_e32 v82, v86, v230
	v_exp_f32_e32 v196, v82
	v_sub_f32_e32 v82, v87, v230
	s_waitcnt lgkmcnt(0)
	v_mfma_f32_32x32x16_bf16 v[98:113], v[98:101], v[174:177], 0
	v_exp_f32_e32 v198, v82
	v_sub_f32_e32 v82, v88, v230
	v_sub_f32_e32 v83, v83, v230
	v_exp_f32_e32 v200, v82
	v_sub_f32_e32 v82, v89, v230
	v_exp_f32_e32 v199, v83
	v_exp_f32_e32 v232, v82
	ds_read_b128 v[188:191], v236 offset:32
	ds_read_b128 v[114:117], v236 offset:12800
	ds_read_b128 v[192:195], v236 offset:12832
	s_add_i32 s4, s4, 1
	v_add_f32_e32 v82, v196, v198
	v_add_f32_e32 v83, v197, v199
	v_add_f32_e32 v84, v200, v232
	v_add_f32_e32 v85, v201, v233
	s_waitcnt lgkmcnt(0)
	v_mfma_f32_32x32x16_bf16 v[114:129], v[114:117], v[174:177], 0
	v_add_f32_e64 v234, v82, v84
	v_add_f32_e64 v235, v83, v85
	v_cvt_pk_bf16_f32 v186, v197, v199
	v_cvt_pk_bf16_f32 v187, v201, v233
	v_add_f32_e32 v235, 0, v235
	v_mfma_f32_32x32x16_bf16 v[98:113], v[188:191], v[170:173], v[98:113]
	ds_read_b128 v[82:85], v236 offset:64
	ds_read_b128 v[86:89], v236 offset:12864
	v_add_f32_e32 v197, v234, v235
	v_cvt_pk_bf16_f32 v188, v196, v198
	v_cvt_pk_bf16_f32 v189, v200, v232
	v_mfma_f32_32x32x16_bf16 v[114:129], v[192:195], v[170:173], v[114:129]
	v_sub_f32_e32 v90, v90, v230
	s_waitcnt lgkmcnt(0)
	v_mfma_f32_32x32x16_bf16 v[98:113], v[82:85], v[166:169], v[98:113]
	v_exp_f32_e32 v190, v90
	v_sub_f32_e32 v90, v91, v230
	v_exp_f32_e32 v192, v90
	v_sub_f32_e32 v90, v92, v230
	v_sub_f32_e32 v82, v93, v230
	v_exp_f32_e32 v191, v90
	v_exp_f32_e32 v193, v82
	ds_read_b128 v[82:85], v236 offset:96
	ds_read_b128 v[90:93], v236 offset:12896
	v_mfma_f32_32x32x16_bf16 v[114:129], v[86:89], v[166:169], v[114:129]
	v_add_f32_e64 v194, v190, v192
	v_add_f32_e64 v195, v191, v193
	v_add_f32_e64 v198, v194, v194
	v_add_f32_e64 v199, v194, v195
	v_cvt_pk_bf16_f32 v190, v190, v192
	v_cvt_pk_bf16_f32 v191, v191, v193
	v_sub_f32_e32 v86, v94, v230
	s_waitcnt lgkmcnt(0)
	v_mfma_f32_32x32x16_bf16 v[98:113], v[82:85], v[162:165], v[98:113]
	v_exp_f32_e32 v94, v86
	v_sub_f32_e32 v86, v95, v230
	v_exp_f32_e32 v192, v86
	v_sub_f32_e32 v86, v96, v230
	v_sub_f32_e32 v82, v97, v230
	v_exp_f32_e32 v96, v86
	v_exp_f32_e32 v193, v82
	ds_read_b128 v[82:85], v236 offset:128
	ds_read_b128 v[86:89], v236 offset:12928
	v_add_f32_e32 v95, v94, v192
	v_cvt_pk_bf16_f32 v192, v94, v192
	v_add_f32_e32 v97, v96, v193
	v_mfma_f32_32x32x16_bf16 v[114:129], v[90:93], v[162:165], v[114:129]
	v_cvt_pk_bf16_f32 v193, v96, v193
	v_sub_f32_e32 v66, v66, v230
	v_exp_f32_e32 v94, v66
	v_sub_f32_e32 v66, v67, v230
	v_exp_f32_e32 v96, v66
	v_sub_f32_e32 v66, v68, v230
	v_exp_f32_e32 v198, v66
	s_waitcnt lgkmcnt(0)
	v_mfma_f32_32x32x16_bf16 v[98:113], v[82:85], v[158:161], v[98:113]
	v_sub_f32_e32 v66, v69, v230
	v_exp_f32_e32 v196, v66
	ds_read_b128 v[66:69], v236 offset:160
	ds_read_b128 v[82:85], v236 offset:12960
	v_add_f32_e32 v90, v94, v96
	v_add_f32_e32 v91, v95, v97
	v_cvt_pk_bf16_f32 v194, v94, v96
	v_add_f32_e32 v92, v198, v196
	v_add_f32_e32 v93, v199, v197
	v_cvt_pk_bf16_f32 v195, v198, v196
	v_mfma_f32_32x32x16_bf16 v[114:129], v[86:89], v[158:161], v[114:129]
	v_add_f32_e64 v90, v90, v92
	v_add_f32_e64 v91, v91, v93
	v_add_f32_e64 v86, v90, v90
	v_add_f32_e64 v87, v90, v91
	v_sub_f32_e32 v70, v70, v230
	v_exp_f32_e32 v88, v70
	v_sub_f32_e32 v70, v71, v230
	s_waitcnt lgkmcnt(0)
	v_mfma_f32_32x32x16_bf16 v[98:113], v[66:69], v[154:157], v[98:113]
	v_exp_f32_e32 v90, v70
	v_sub_f32_e32 v70, v72, v230
	v_sub_f32_e32 v66, v73, v230
	v_exp_f32_e32 v89, v70
	v_exp_f32_e32 v91, v66
	ds_read_b128 v[66:69], v236 offset:192
	ds_read_b128 v[70:73], v236 offset:12992
	v_cvt_pk_bf16_f32 v196, v88, v90
	v_mfma_f32_32x32x16_bf16 v[114:129], v[82:85], v[154:157], v[114:129]
	v_add_f32_e64 v92, v88, v90
	v_add_f32_e64 v93, v89, v91
	v_cvt_pk_bf16_f32 v197, v89, v91
	v_add_f32_e32 v93, v92, v93
	v_add_f32_e32 v92, v92, v92
	v_sub_f32_e32 v74, v74, v230
	s_waitcnt lgkmcnt(0)
	v_mfma_f32_32x32x16_bf16 v[98:113], v[66:69], v[150:153], v[98:113]
	v_exp_f32_e32 v82, v74
	v_sub_f32_e32 v74, v75, v230
	v_exp_f32_e32 v84, v74
	v_sub_f32_e32 v74, v76, v230
	v_sub_f32_e32 v66, v77, v230
	v_exp_f32_e32 v86, v74
	v_exp_f32_e32 v88, v66
	ds_read_b128 v[66:69], v236 offset:224
	ds_read_b128 v[74:77], v236 offset:13024
	v_add_f32_e32 v83, v82, v84
	v_cvt_pk_bf16_f32 v198, v82, v84
	v_add_f32_e32 v85, v86, v88
	v_mfma_f32_32x32x16_bf16 v[114:129], v[70:73], v[150:153], v[114:129]
	v_cvt_pk_bf16_f32 v199, v86, v88
	v_sub_f32_e32 v70, v78, v230
	v_exp_f32_e32 v82, v70
	v_sub_f32_e32 v70, v79, v230
	s_waitcnt lgkmcnt(0)
; #define LAS __attribute__((address_space(3)))
; __device__ __forceinline__ unsigned cvt_pk(float lo, float hi) { unsigned r; asm volatile("v_cvt_pk_bf16_f32 %0, %1, %2" : "=v"(r) : "v"(lo), "v"(hi)); return r; }
; __device__ __forceinline__ void attn_unit(LAS unsigned char* lds, int b, int h, int q0, int kbeg, int ntiles, const bf16_t* Q, const bf16_t* K, const bf16_t* Vt, bf16_t* cat) {
;     ...
;         for (int ds = 0; ds < 12; ++ds) {
;             bf16x8 na = ka, nb = kbb;
;             if (ds < 11) { na = *(const LAS bf16x8*)(kb + (ds + 1) * 32); nb = *(const LAS bf16x8*)(kb + 32 * (KP * 2) + (ds + 1) * 32); }
;             pn0 = __builtin_amdgcn_mfma_f32_32x32x16_bf16(ka, qf[ds], pn0, 0, 0, 0);
;             pn1 = __builtin_amdgcn_mfma_f32_32x32x16_bf16(kbb, qf[ds], pn1, 0, 0, 0);
;             if (ds < 8) {
;                 float e[4];
; #pragma unroll
;                 for (int j = 0; j < 4; ++j) { const float v = ds < 4 ? pc0[4 * ds + j] : pc1[4 * (ds - 4) + j]; e[j] = __builtin_amdgcn_exp2f(v - mrun); }
;                 ps += (e[0] + e[1]) + (e[2] + e[3]);
;                 const unsigned w0 = cvt_pk(e[0], e[1]), w1 = cvt_pk(e[2], e[3]);
;                 if ((ds & 1) == 0) { pw[ds >> 1].x = w0; pw[ds >> 1].y = w1; } else { pw[ds >> 1].z = w0; pw[ds >> 1].w = w1; }
;             }
;             ka = na; kbb = nb;
;             __builtin_amdgcn_sched_barrier(0);
;         }
;         lrun += ps;
;         const LAS unsigned char* vb = lds + 2 * AK_BYTES + buf * AV_BYTES + r32 * AV_PITCH + hi * 8;
; #pragma unroll
;         for (int d = 0; d < 4; ++d)
; #pragma unroll
;             for (int ks = 0; ks < 4; ++ks) {
;                 const s16x4 lo = *(const LAS s16x4*)(vb + d * 32 * AV_PITCH + ks * 32), hh = *(const LAS s16x4*)(vb + d * 32 * AV_PITCH + ks * 32 + 16);
;                 const bf16x8 vf = (bf16x8){lo[0], lo[1], lo[2], lo[3], hh[0], hh[1], hh[2], hh[3]};
;                 o[d] = __builtin_amdgcn_mfma_f32_32x32x16_bf16(vf, __builtin_bit_cast(bf16x8, pw[ks]), o[d], 0, 0, 0);
;             }
;         { float mx = fmaxf(pn0[0], pn1[0]);
; #pragma unroll
;           for (int r = 1; r < 16; ++r) mx = fmaxf(mx, fmaxf(pn0[r], pn1[r]));
;           mxc = fmaxf(mx, __shfl_xor(mx, 32)); }
;         if (kt + 1 < ntiles) ASTOREV(buf ^ 1);
;         asm volatile("s_waitcnt vmcnt(0)" ::: "memory");
;         __syncthreads();
	v_mfma_f32_32x32x16_bf16 v[98:113], v[66:69], v[146:149], v[98:113]
	v_exp_f32_e32 v84, v70
	v_sub_f32_e32 v70, v80, v230
	v_sub_f32_e32 v66, v81, v230
	v_exp_f32_e32 v92, v70
	v_exp_f32_e32 v86, v66
	ds_read_b128 v[66:69], v236 offset:256
	ds_read_b128 v[70:73], v236 offset:13056
	v_add_f32_e32 v78, v82, v84
	v_add_f32_e32 v79, v83, v85
	v_mfma_f32_32x32x16_bf16 v[114:129], v[74:77], v[146:149], v[114:129]
	v_add_f32_e64 v80, v92, v86
	v_add_f32_e64 v81, v93, v87
	v_cvt_pk_bf16_f32 v200, v82, v84
	v_cvt_pk_bf16_f32 v201, v92, v86
	v_add_f32_e64 v78, v78, v80
	v_add_f32_e64 v79, v79, v81
	v_add_f32_e32 v237, v78, v79
	s_waitcnt lgkmcnt(0)
	v_mfma_f32_32x32x16_bf16 v[98:113], v[66:69], v[142:145], v[98:113]
	ds_read_b128 v[66:69], v236 offset:288
	ds_read_b128 v[74:77], v236 offset:13088
	v_mfma_f32_32x32x16_bf16 v[114:129], v[70:73], v[142:145], v[114:129]
	s_waitcnt lgkmcnt(0)
	v_mfma_f32_32x32x16_bf16 v[98:113], v[66:69], v[138:141], v[98:113]
	ds_read_b128 v[66:69], v236 offset:320
	ds_read_b128 v[70:73], v236 offset:13120
	v_mfma_f32_32x32x16_bf16 v[114:129], v[74:77], v[138:141], v[114:129]
	s_waitcnt lgkmcnt(0)
	v_mfma_f32_32x32x16_bf16 v[98:113], v[66:69], v[134:137], v[98:113]
	ds_read_b128 v[66:69], v236 offset:352
	ds_read_b128 v[232:235], v236 offset:13152
	v_mfma_f32_32x32x16_bf16 v[114:129], v[70:73], v[134:137], v[114:129]
	s_waitcnt lgkmcnt(0)
	v_mfma_f32_32x32x16_bf16 v[82:97], v[66:69], v[130:133], v[98:113]
	v_mfma_f32_32x32x16_bf16 v[66:81], v[232:235], v[130:133], v[114:129]
	s_mulk_i32 s5, 0x4400
	v_add_u32_e32 v232, s5, v229
	v_add_u32_e32 v250, 0xc800, v232
	v_add_u32_e32 v251, 0xd800, v232
	v_add_u32_e32 v252, 0xe800, v232
	v_add_u32_e32 v253, 0xf800, v232
	s_mulk_i32 s6, 0x4400
	ds_read2_b64 v[98:101], v250 offset1:2
	ds_read2_b64 v[102:105], v251 offset0:32 offset1:34
	ds_read2_b64 v[106:109], v252 offset0:64 offset1:66
	ds_read2_b64 v[110:113], v253 offset0:96 offset1:98
	ds_read2_b64 v[114:117], v250 offset0:4 offset1:6
	ds_read2_b64 v[118:121], v251 offset0:36 offset1:38
	ds_read2_b64 v[122:125], v252 offset0:68 offset1:70
	ds_read2_b64 v[126:129], v253 offset0:100 offset1:102
	v_add_f32_e32 v202, v202, v237
	v_max3_f32 v254, v82, v66, v83
	v_max3_f32 v254, v254, v67, v84
	v_max3_f32 v254, v254, v68, v85
	v_max3_f32 v254, v254, v69, v86
	s_waitcnt lgkmcnt(7)
	v_mfma_f32_32x32x16_bf16 v[50:65], v[98:101], v[186:189], v[50:65]
	ds_read2_b64 v[98:101], v250 offset0:8 offset1:10
	v_max3_f32 v254, v254, v70, v87
	v_max3_f32 v254, v254, v71, v88
	s_waitcnt lgkmcnt(7)
	v_mfma_f32_32x32x16_bf16 v[34:49], v[102:105], v[186:189], v[34:49]
	ds_read2_b64 v[102:105], v251 offset0:40 offset1:42
	v_max3_f32 v254, v254, v72, v89
	v_max3_f32 v254, v254, v73, v90
	s_waitcnt lgkmcnt(7)
	v_mfma_f32_32x32x16_bf16 v[18:33], v[106:109], v[186:189], v[18:33]
	ds_read2_b64 v[106:109], v252 offset0:72 offset1:74
	v_max3_f32 v254, v254, v74, v91
	v_max3_f32 v254, v254, v75, v92
	s_waitcnt lgkmcnt(7)
	v_mfma_f32_32x32x16_bf16 v[2:17], v[110:113], v[186:189], v[2:17]
	ds_read2_b64 v[110:113], v253 offset0:104 offset1:106
	v_max3_f32 v254, v254, v76, v93
	v_max3_f32 v254, v254, v77, v94
	s_waitcnt lgkmcnt(7)
	v_mfma_f32_32x32x16_bf16 v[50:65], v[114:117], v[190:193], v[50:65]
	ds_read2_b64 v[114:117], v250 offset0:12 offset1:14
	v_max3_f32 v254, v254, v78, v95
	v_max3_f32 v254, v254, v79, v96
	s_waitcnt lgkmcnt(7)
	v_mfma_f32_32x32x16_bf16 v[34:49], v[118:121], v[190:193], v[34:49]
	ds_read2_b64 v[118:121], v251 offset0:44 offset1:46
	v_max3_f32 v254, v254, v80, v97
	v_max_f32_e32 v254, v254, v81
	s_waitcnt lgkmcnt(7)
	v_mfma_f32_32x32x16_bf16 v[18:33], v[122:125], v[190:193], v[18:33]
	ds_read2_b64 v[122:125], v252 offset0:76 offset1:78
	v_lshl_add_u64 v[212:213], v[212:213], 0, s[60:61]
	v_lshl_add_u64 v[214:215], v[214:215], 0, s[60:61]
	s_waitcnt lgkmcnt(7)
	v_mfma_f32_32x32x16_bf16 v[2:17], v[126:129], v[190:193], v[2:17]
	ds_read2_b64 v[126:129], v253 offset0:108 offset1:110
	v_lshl_add_u64 v[216:217], v[216:217], 0, s[60:61]
	v_lshl_add_u64 v[218:219], v[218:219], 0, s[60:61]
	v_lshl_add_u64 v[220:221], v[220:221], 0, s[66:67]
	ds_bpermute_b32 v255, v207, v254
	s_waitcnt lgkmcnt(8)
	v_mfma_f32_32x32x16_bf16 v[50:65], v[98:101], v[194:197], v[50:65]
	s_waitcnt lgkmcnt(7)
	v_mfma_f32_32x32x16_bf16 v[34:49], v[102:105], v[194:197], v[34:49]
	s_waitcnt lgkmcnt(6)
	v_mfma_f32_32x32x16_bf16 v[18:33], v[106:109], v[194:197], v[18:33]
	s_waitcnt lgkmcnt(5)
	v_mfma_f32_32x32x16_bf16 v[2:17], v[110:113], v[194:197], v[2:17]
	s_waitcnt lgkmcnt(0)
	v_max_f32_e32 v255, v255, v255
	v_max_f32_e32 v98, v254, v255
	v_add_u32_e32 v255, s6, v231
	v_add_u32_e32 v238, 0xc800, v255
	v_add_u32_e32 v255, 0xea00, v255
	s_cmp_lg_u32 s4, 34
	s_waitcnt vmcnt(0)
	ds_write2_b64 v238, v[178:179], v[180:181] offset1:1
	ds_write2_b64 v255, v[182:183], v[184:185] offset1:1
	s_waitcnt vmcnt(0)
	s_waitcnt lgkmcnt(0)
	s_barrier
	v_mfma_f32_32x32x16_bf16 v[50:65], v[114:117], v[198:201], v[50:65]
	v_mfma_f32_32x32x16_bf16 v[34:49], v[118:121], v[198:201], v[34:49]
	v_mfma_f32_32x32x16_bf16 v[18:33], v[122:125], v[198:201], v[18:33]
	v_mfma_f32_32x32x16_bf16 v[2:17], v[126:129], v[198:201], v[2:17]
	s_cbranch_scc0 .LBB0_819

; #define LAS __attribute__((address_space(3)))
; __device__ __forceinline__ unsigned cvt_pk(float lo, float hi) { unsigned r; asm volatile("v_cvt_pk_bf16_f32 %0, %1, %2" : "=v"(r) : "v"(lo), "v"(hi)); return r; }
; __device__ __forceinline__ void attn_unit(LAS unsigned char* lds, int b, int h, int q0, int kbeg, int ntiles, const bf16_t* Q, const bf16_t* K, const bf16_t* Vt, bf16_t* cat) {
;     ...
;         const LAS unsigned char* kb = lds + (buf ^ 1) * AK_BYTES + r32 * (KP * 2) + hi * 16;
;         f32x16 pn0, pn1;
; #pragma unroll
;         for (int r = 0; r < 16; ++r) { pn0[r] = 0.f; pn1[r] = 0.f; }
;         float ps = 0.f; u32x4 pw[4];
;         bf16x8 ka = *(const LAS bf16x8*)(kb), kbb = *(const LAS bf16x8*)(kb + 32 * (KP * 2));
; #pragma unroll
;         for (int ds = 0; ds < 12; ++ds) {
;             bf16x8 na = ka, nb = kbb;
;             if (ds < 11) { na = *(const LAS bf16x8*)(kb + (ds + 1) * 32); nb = *(const LAS bf16x8*)(kb + 32 * (KP * 2) + (ds + 1) * 32); }
;             pn0 = __builtin_amdgcn_mfma_f32_32x32x16_bf16(ka, qf[ds], pn0, 0, 0, 0);
;             pn1 = __builtin_amdgcn_mfma_f32_32x32x16_bf16(kbb, qf[ds], pn1, 0, 0, 0);
;             if (ds < 8) {
;                 float e[4];
; #pragma unroll
;                 for (int j = 0; j < 4; ++j) { const float v = ds < 4 ? pc0[4 * ds + j] : pc1[4 * (ds - 4) + j]; e[j] = __builtin_amdgcn_exp2f(v - mrun); }
;                 ps += (e[0] + e[1]) + (e[2] + e[3]);
;                 const unsigned w0 = cvt_pk(e[0], e[1]), w1 = cvt_pk(e[2], e[3]);
;                 if ((ds & 1) == 0) { pw[ds >> 1].x = w0; pw[ds >> 1].y = w1; } else { pw[ds >> 1].z = w0; pw[ds >> 1].w = w1; }
;             }
;             ka = na; kbb = nb;
;             __builtin_amdgcn_sched_barrier(0);
;         }
.LBB0_1840:
	s_xor_b32 s6, s5, 1
	s_mul_i32 s7, s6, 0x6400
	v_add_u32_e32 v233, s7, v229
	ds_read_b128 v[98:101], v233
	v_sub_f32_e32 v82, v82, v231
	v_exp_f32_e32 v197, v82
	v_sub_f32_e32 v82, v84, v231
	v_exp_f32_e32 v201, v82
	v_sub_f32_e32 v82, v85, v231
	v_exp_f32_e32 v235, v82
	v_sub_f32_e32 v82, v86, v231
	v_exp_f32_e32 v196, v82
	v_sub_f32_e32 v82, v87, v231
	s_waitcnt lgkmcnt(0)
	v_mfma_f32_32x32x16_bf16 v[98:113], v[98:101], v[174:177], 0
	v_exp_f32_e32 v198, v82
	v_sub_f32_e32 v82, v88, v231
	v_sub_f32_e32 v83, v83, v231
	v_exp_f32_e32 v200, v82
	v_sub_f32_e32 v82, v89, v231
	v_exp_f32_e32 v199, v83
	v_exp_f32_e32 v234, v82
	ds_read_b128 v[188:191], v233 offset:32
	ds_read_b128 v[114:117], v233 offset:12800
	ds_read_b128 v[192:195], v233 offset:12832
	s_add_i32 s4, s4, 1
	v_add_f32_e32 v82, v196, v198
	v_add_f32_e32 v83, v197, v199
	v_add_f32_e32 v84, v200, v234
	v_add_f32_e32 v85, v201, v235
	s_waitcnt lgkmcnt(0)
	v_mfma_f32_32x32x16_bf16 v[114:129], v[114:117], v[174:177], 0
	v_add_f32_e64 v236, v82, v84
	v_add_f32_e64 v237, v83, v85
	v_cvt_pk_bf16_f32 v186, v197, v199
	v_cvt_pk_bf16_f32 v187, v201, v235
	v_add_f32_e32 v237, 0, v237
	v_mfma_f32_32x32x16_bf16 v[98:113], v[188:191], v[170:173], v[98:113]
	ds_read_b128 v[82:85], v233 offset:64
	ds_read_b128 v[86:89], v233 offset:12864
	v_add_f32_e32 v197, v236, v237
	v_cvt_pk_bf16_f32 v188, v196, v198
	v_cvt_pk_bf16_f32 v189, v200, v234
	v_mfma_f32_32x32x16_bf16 v[114:129], v[192:195], v[170:173], v[114:129]
	v_sub_f32_e32 v90, v90, v231
	s_waitcnt lgkmcnt(0)
	v_mfma_f32_32x32x16_bf16 v[98:113], v[82:85], v[166:169], v[98:113]
	v_exp_f32_e32 v190, v90
	v_sub_f32_e32 v90, v91, v231
	v_exp_f32_e32 v192, v90
	v_sub_f32_e32 v90, v92, v231
	v_sub_f32_e32 v82, v93, v231
	v_exp_f32_e32 v191, v90
	v_exp_f32_e32 v193, v82
	ds_read_b128 v[82:85], v233 offset:96
	ds_read_b128 v[90:93], v233 offset:12896
	v_mfma_f32_32x32x16_bf16 v[114:129], v[86:89], v[166:169], v[114:129]
	v_add_f32_e64 v194, v190, v192
	v_add_f32_e64 v195, v191, v193
	v_add_f32_e64 v198, v194, v194
	v_add_f32_e64 v199, v194, v195
	v_cvt_pk_bf16_f32 v190, v190, v192
	v_cvt_pk_bf16_f32 v191, v191, v193
	v_sub_f32_e32 v86, v94, v231
	s_waitcnt lgkmcnt(0)
	v_mfma_f32_32x32x16_bf16 v[98:113], v[82:85], v[162:165], v[98:113]
	v_exp_f32_e32 v94, v86
	v_sub_f32_e32 v86, v95, v231
	v_exp_f32_e32 v192, v86
	v_sub_f32_e32 v86, v96, v231
	v_sub_f32_e32 v82, v97, v231
	v_exp_f32_e32 v96, v86
	v_exp_f32_e32 v193, v82
	ds_read_b128 v[82:85], v233 offset:128
	ds_read_b128 v[86:89], v233 offset:12928
	v_add_f32_e32 v95, v94, v192
	v_cvt_pk_bf16_f32 v192, v94, v192
	v_add_f32_e32 v97, v96, v193
	v_mfma_f32_32x32x16_bf16 v[114:129], v[90:93], v[162:165], v[114:129]
	v_cvt_pk_bf16_f32 v193, v96, v193
	v_sub_f32_e32 v66, v66, v231
	v_exp_f32_e32 v94, v66
	v_sub_f32_e32 v66, v67, v231
	v_exp_f32_e32 v96, v66
	v_sub_f32_e32 v66, v68, v231
	v_exp_f32_e32 v198, v66
	s_waitcnt lgkmcnt(0)
	v_mfma_f32_32x32x16_bf16 v[98:113], v[82:85], v[158:161], v[98:113]
	v_sub_f32_e32 v66, v69, v231
	v_exp_f32_e32 v196, v66
	ds_read_b128 v[66:69], v233 offset:160
	ds_read_b128 v[82:85], v233 offset:12960
	v_add_f32_e32 v90, v94, v96
	v_add_f32_e32 v91, v95, v97
	v_cvt_pk_bf16_f32 v194, v94, v96
	v_add_f32_e32 v92, v198, v196
	v_add_f32_e32 v93, v199, v197
	v_cvt_pk_bf16_f32 v195, v198, v196
	v_mfma_f32_32x32x16_bf16 v[114:129], v[86:89], v[158:161], v[114:129]
	v_add_f32_e64 v90, v90, v92
	v_add_f32_e64 v91, v91, v93
	v_add_f32_e64 v86, v90, v90
	v_add_f32_e64 v87, v90, v91
	v_sub_f32_e32 v70, v70, v231
	v_exp_f32_e32 v88, v70
	v_sub_f32_e32 v70, v71, v231
	s_waitcnt lgkmcnt(0)
	v_mfma_f32_32x32x16_bf16 v[98:113], v[66:69], v[154:157], v[98:113]
	v_exp_f32_e32 v90, v70
	v_sub_f32_e32 v70, v72, v231
	v_sub_f32_e32 v66, v73, v231
	v_exp_f32_e32 v89, v70
	v_exp_f32_e32 v91, v66
	ds_read_b128 v[66:69], v233 offset:192
	ds_read_b128 v[70:73], v233 offset:12992
	v_cvt_pk_bf16_f32 v196, v88, v90
	v_mfma_f32_32x32x16_bf16 v[114:129], v[82:85], v[154:157], v[114:129]
	v_add_f32_e64 v92, v88, v90
	v_add_f32_e64 v93, v89, v91
	v_cvt_pk_bf16_f32 v197, v89, v91
	v_add_f32_e32 v93, v92, v93
	v_add_f32_e32 v92, v92, v92
	v_sub_f32_e32 v74, v74, v231
	s_waitcnt lgkmcnt(0)
	v_mfma_f32_32x32x16_bf16 v[98:113], v[66:69], v[150:153], v[98:113]
	v_exp_f32_e32 v82, v74
	v_sub_f32_e32 v74, v75, v231
	v_exp_f32_e32 v84, v74
	v_sub_f32_e32 v74, v76, v231
	v_sub_f32_e32 v66, v77, v231
	v_exp_f32_e32 v86, v74
	v_exp_f32_e32 v88, v66
	ds_read_b128 v[66:69], v233 offset:224
	ds_read_b128 v[74:77], v233 offset:13024
	v_add_f32_e32 v83, v82, v84
	v_cvt_pk_bf16_f32 v198, v82, v84
	v_add_f32_e32 v85, v86, v88
	v_mfma_f32_32x32x16_bf16 v[114:129], v[70:73], v[150:153], v[114:129]
	v_cvt_pk_bf16_f32 v199, v86, v88
	v_sub_f32_e32 v70, v78, v231
	v_exp_f32_e32 v82, v70
	v_sub_f32_e32 v70, v79, v231
	s_waitcnt lgkmcnt(0)
; #define LAS __attribute__((address_space(3)))
; __device__ __forceinline__ unsigned cvt_pk(float lo, float hi) { unsigned r; asm volatile("v_cvt_pk_bf16_f32 %0, %1, %2" : "=v"(r) : "v"(lo), "v"(hi)); return r; }
; __device__ __forceinline__ void attn_unit(LAS unsigned char* lds, int b, int h, int q0, int kbeg, int ntiles, const bf16_t* Q, const bf16_t* K, const bf16_t* Vt, bf16_t* cat) {
;     ...
;         for (int ds = 0; ds < 12; ++ds) {
;             bf16x8 na = ka, nb = kbb;
;             if (ds < 11) { na = *(const LAS bf16x8*)(kb + (ds + 1) * 32); nb = *(const LAS bf16x8*)(kb + 32 * (KP * 2) + (ds + 1) * 32); }
;             pn0 = __builtin_amdgcn_mfma_f32_32x32x16_bf16(ka, qf[ds], pn0, 0, 0, 0);
;             pn1 = __builtin_amdgcn_mfma_f32_32x32x16_bf16(kbb, qf[ds], pn1, 0, 0, 0);
;             if (ds < 8) {
;                 float e[4];
; #pragma unroll
;                 for (int j = 0; j < 4; ++j) { const float v = ds < 4 ? pc0[4 * ds + j] : pc1[4 * (ds - 4) + j]; e[j] = __builtin_amdgcn_exp2f(v - mrun); }
;                 ps += (e[0] + e[1]) + (e[2] + e[3]);
;                 const unsigned w0 = cvt_pk(e[0], e[1]), w1 = cvt_pk(e[2], e[3]);
;                 if ((ds & 1) == 0) { pw[ds >> 1].x = w0; pw[ds >> 1].y = w1; } else { pw[ds >> 1].z = w0; pw[ds >> 1].w = w1; }
;             }
;             ka = na; kbb = nb;
;             __builtin_amdgcn_sched_barrier(0);
;         }
;         lrun += ps;
;         const LAS unsigned char* vb = lds + 2 * AK_BYTES + buf * AV_BYTES + r32 * AV_PITCH + hi * 8;
; #pragma unroll
;         for (int d = 0; d < 4; ++d)
; #pragma unroll
;             for (int ks = 0; ks < 4; ++ks) {
;                 const s16x4 lo = *(const LAS s16x4*)(vb + d * 32 * AV_PITCH + ks * 32), hh = *(const LAS s16x4*)(vb + d * 32 * AV_PITCH + ks * 32 + 16);
;                 const bf16x8 vf = (bf16x8){lo[0], lo[1], lo[2], lo[3], hh[0], hh[1], hh[2], hh[3]};
;                 o[d] = __builtin_amdgcn_mfma_f32_32x32x16_bf16(vf, __builtin_bit_cast(bf16x8, pw[ks]), o[d], 0, 0, 0);
;             }
;         { float mx = fmaxf(pn0[0], pn1[0]);
; #pragma unroll
;           for (int r = 1; r < 16; ++r) mx = fmaxf(mx, fmaxf(pn0[r], pn1[r]));
;           mxc = fmaxf(mx, __shfl_xor(mx, 32)); }
;         if (kt + 1 < ntiles) ASTOREV(buf ^ 1);
;         asm volatile("s_waitcnt vmcnt(0)" ::: "memory");
;         __syncthreads();
	v_mfma_f32_32x32x16_bf16 v[98:113], v[66:69], v[146:149], v[98:113]
	v_exp_f32_e32 v84, v70
	v_sub_f32_e32 v70, v80, v231
	v_sub_f32_e32 v66, v81, v231
	v_exp_f32_e32 v92, v70
	v_exp_f32_e32 v86, v66
	ds_read_b128 v[66:69], v233 offset:256
	ds_read_b128 v[70:73], v233 offset:13056
	v_add_f32_e32 v78, v82, v84
	v_add_f32_e32 v79, v83, v85
	v_mfma_f32_32x32x16_bf16 v[114:129], v[74:77], v[146:149], v[114:129]
	v_add_f32_e64 v80, v92, v86
	v_add_f32_e64 v81, v93, v87
	v_cvt_pk_bf16_f32 v200, v82, v84
	v_cvt_pk_bf16_f32 v201, v92, v86
	v_add_f32_e64 v78, v78, v80
	v_add_f32_e64 v79, v79, v81
	v_add_f32_e32 v238, v78, v79
	s_waitcnt lgkmcnt(0)
	v_mfma_f32_32x32x16_bf16 v[98:113], v[66:69], v[142:145], v[98:113]
	ds_read_b128 v[66:69], v233 offset:288
	ds_read_b128 v[74:77], v233 offset:13088
	v_mfma_f32_32x32x16_bf16 v[114:129], v[70:73], v[142:145], v[114:129]
	s_waitcnt lgkmcnt(0)
	v_mfma_f32_32x32x16_bf16 v[98:113], v[66:69], v[138:141], v[98:113]
	ds_read_b128 v[66:69], v233 offset:320
	ds_read_b128 v[70:73], v233 offset:13120
	v_mfma_f32_32x32x16_bf16 v[114:129], v[74:77], v[138:141], v[114:129]
	s_waitcnt lgkmcnt(0)
	v_mfma_f32_32x32x16_bf16 v[98:113], v[66:69], v[134:137], v[98:113]
	ds_read_b128 v[66:69], v233 offset:352
	ds_read_b128 v[234:237], v233 offset:13152
	v_mfma_f32_32x32x16_bf16 v[114:129], v[70:73], v[134:137], v[114:129]
	s_waitcnt lgkmcnt(0)
	v_mfma_f32_32x32x16_bf16 v[82:97], v[66:69], v[130:133], v[98:113]
	v_mfma_f32_32x32x16_bf16 v[66:81], v[234:237], v[130:133], v[114:129]
	s_mulk_i32 s5, 0x4400
	v_add_u32_e32 v233, s5, v230
	v_add_u32_e32 v250, 0xc800, v233
	v_add_u32_e32 v251, 0xd800, v233
	v_add_u32_e32 v252, 0xe800, v233
	v_add_u32_e32 v253, 0xf800, v233
	s_mulk_i32 s6, 0x4400
	ds_read2_b64 v[98:101], v250 offset1:2
	ds_read2_b64 v[102:105], v251 offset0:32 offset1:34
	ds_read2_b64 v[106:109], v252 offset0:64 offset1:66
	ds_read2_b64 v[110:113], v253 offset0:96 offset1:98
	ds_read2_b64 v[114:117], v250 offset0:4 offset1:6
	ds_read2_b64 v[118:121], v251 offset0:36 offset1:38
	ds_read2_b64 v[122:125], v252 offset0:68 offset1:70
	ds_read2_b64 v[126:129], v253 offset0:100 offset1:102
	v_add_f32_e32 v202, v202, v238
	v_max3_f32 v254, v82, v66, v83
	v_max3_f32 v254, v254, v67, v84
	v_max3_f32 v254, v254, v68, v85
	v_max3_f32 v254, v254, v69, v86
	s_waitcnt lgkmcnt(7)
	v_mfma_f32_32x32x16_bf16 v[50:65], v[98:101], v[186:189], v[50:65]
	ds_read2_b64 v[98:101], v250 offset0:8 offset1:10
	v_max3_f32 v254, v254, v70, v87
	v_max3_f32 v254, v254, v71, v88
	s_waitcnt lgkmcnt(7)
	v_mfma_f32_32x32x16_bf16 v[34:49], v[102:105], v[186:189], v[34:49]
	ds_read2_b64 v[102:105], v251 offset0:40 offset1:42
	v_max3_f32 v254, v254, v72, v89
	v_max3_f32 v254, v254, v73, v90
	s_waitcnt lgkmcnt(7)
	v_mfma_f32_32x32x16_bf16 v[18:33], v[106:109], v[186:189], v[18:33]
	ds_read2_b64 v[106:109], v252 offset0:72 offset1:74
	v_max3_f32 v254, v254, v74, v91
	v_max3_f32 v254, v254, v75, v92
	s_waitcnt lgkmcnt(7)
	v_mfma_f32_32x32x16_bf16 v[2:17], v[110:113], v[186:189], v[2:17]
	ds_read2_b64 v[110:113], v253 offset0:104 offset1:106
	v_max3_f32 v254, v254, v76, v93
	v_max3_f32 v254, v254, v77, v94
	s_waitcnt lgkmcnt(7)
	v_mfma_f32_32x32x16_bf16 v[50:65], v[114:117], v[190:193], v[50:65]
	ds_read2_b64 v[114:117], v250 offset0:12 offset1:14
	v_max3_f32 v254, v254, v78, v95
	v_max3_f32 v254, v254, v79, v96
	s_waitcnt lgkmcnt(7)
	v_mfma_f32_32x32x16_bf16 v[34:49], v[118:121], v[190:193], v[34:49]
	ds_read2_b64 v[118:121], v251 offset0:44 offset1:46
	v_max3_f32 v254, v254, v80, v97
	v_max_f32_e32 v254, v254, v81
	s_waitcnt lgkmcnt(7)
	v_mfma_f32_32x32x16_bf16 v[18:33], v[122:125], v[190:193], v[18:33]
	ds_read2_b64 v[122:125], v252 offset0:76 offset1:78
	v_lshl_add_u64 v[214:215], v[214:215], 0, s[38:39]
	v_lshl_add_u64 v[216:217], v[216:217], 0, s[38:39]
	s_waitcnt lgkmcnt(7)
	v_mfma_f32_32x32x16_bf16 v[2:17], v[126:129], v[190:193], v[2:17]
	ds_read2_b64 v[126:129], v253 offset0:108 offset1:110
	v_lshl_add_u64 v[218:219], v[218:219], 0, s[38:39]
	v_lshl_add_u64 v[220:221], v[220:221], 0, s[38:39]
	v_lshl_add_u64 v[222:223], v[222:223], 0, s[40:41]
	ds_bpermute_b32 v255, v209, v254
	s_waitcnt lgkmcnt(8)
	v_mfma_f32_32x32x16_bf16 v[50:65], v[98:101], v[194:197], v[50:65]
	s_waitcnt lgkmcnt(7)
	v_mfma_f32_32x32x16_bf16 v[34:49], v[102:105], v[194:197], v[34:49]
	s_waitcnt lgkmcnt(6)
	v_mfma_f32_32x32x16_bf16 v[18:33], v[106:109], v[194:197], v[18:33]
	s_waitcnt lgkmcnt(5)
	v_mfma_f32_32x32x16_bf16 v[2:17], v[110:113], v[194:197], v[2:17]
	s_waitcnt lgkmcnt(0)
	v_max_f32_e32 v255, v255, v255
	v_max_f32_e32 v98, v254, v255
	v_add_u32_e32 v255, s6, v232
	v_add_u32_e32 v239, 0xc800, v255
	v_add_u32_e32 v255, 0xea00, v255
	s_cmp_lg_u32 s4, 34
	s_waitcnt vmcnt(0)
	ds_write2_b64 v239, v[178:179], v[180:181] offset1:1
	ds_write2_b64 v255, v[182:183], v[184:185] offset1:1
	s_waitcnt vmcnt(0)
	s_waitcnt lgkmcnt(0)
	s_barrier
	v_mfma_f32_32x32x16_bf16 v[50:65], v[114:117], v[198:201], v[50:65]
	v_mfma_f32_32x32x16_bf16 v[34:49], v[118:121], v[198:201], v[34:49]
	v_mfma_f32_32x32x16_bf16 v[18:33], v[122:125], v[198:201], v[18:33]
	v_mfma_f32_32x32x16_bf16 v[2:17], v[126:129], v[198:201], v[2:17]
	s_cbranch_scc0 .LBB0_1845
